# attention loop: removed 32 dead address SALU/VALU ops left by the V-load merge, on top of v32
# baseline (speedup 1.0000x reference)
; __device__ __forceinline__ void attn_item(const Params& p, int l, int hs, int idx) {
;     ...
;     for (int i = 0; i < ntot; i += 2) {
;         const int i1 = (i + 1 < ntot) ? i + 1 : i;
;         ATT_LOAD(i1, kfb, vlb, vhb);
;         ATT_COMPUTE(i, kfa, vla, vha);
;         const int i2 = (i + 2 < ntot) ? i + 2 : i;
;         ATT_LOAD(i2, kfa, vla, vha);
.LBB0_152:
	s_add_i32 s42, s38, 1
	s_cmp_lt_u32 s42, s36
	s_cselect_b64 s[34:35], -1, 0
	s_and_b64 s[6:7], s[34:35], exec
	s_cselect_b32 s24, s42, s38
	s_cmp_lt_i32 s24, s40
	s_cbranch_scc1 .LBB0_154
	s_sub_i32 s24, s24, s40
	s_mov_b64 s[8:9], 0x6000
	s_mov_b64 s[12:13], 0x4000
	s_mov_b64 s[18:19], 0x2000
	s_mov_b64 s[22:23], s[84:85]
	s_mov_b64 s[20:21], s[0:1]
	v_mov_b64_e32 v[92:93], v[188:189]
	s_branch .LBB0_155
.LBB0_154:
	s_mov_b64 s[8:9], 0x30000
	s_mov_b64 s[12:13], 0x20000
	s_mov_b64 s[18:19], 0x10000
	s_mov_b64 s[22:23], s[4:5]
	s_mov_b64 s[20:21], s[94:95]
	v_mov_b64_e32 v[92:93], v[190:191]
.LBB0_155:
	s_waitcnt vmcnt(0)
	ds_read_b128 v[144:147], v216
	ds_read_b128 v[140:143], v216 offset:1024
	ds_read_b128 v[136:139], v216 offset:2048
	ds_read_b128 v[132:135], v216 offset:3072
	ds_read_b128 v[84:87], v216 offset:4096
	ds_read_b128 v[76:79], v216 offset:5120
	ds_read_b128 v[72:75], v216 offset:6144
	ds_read_b128 v[68:71], v216 offset:7168
	s_waitcnt lgkmcnt(4)
	v_mfma_f32_16x16x32_bf16 v[104:107], v[144:147], v[20:23], 0
	s_lshl_b32 s25, s24, 6
	s_add_u32 s20, s20, s25
	s_addc_u32 s21, s21, 0
	v_mfma_f32_16x16x32_bf16 v[176:179], v[140:143], v[24:27], v[104:107]
	s_add_u32 s18, s20, s18
	s_addc_u32 s19, s21, s19
	v_mfma_f32_16x16x32_bf16 v[104:107], v[144:147], v[28:31], 0
	s_add_u32 s12, s20, s12
	s_addc_u32 s13, s21, s13
	v_mfma_f32_16x16x32_bf16 v[168:171], v[140:143], v[32:35], v[104:107]
	s_add_u32 s8, s20, s8
	v_mfma_f32_16x16x32_bf16 v[104:107], v[144:147], v[36:39], 0
	s_addc_u32 s9, s21, s9
	v_lshl_add_u64 v[94:95], v[192:193], 0, s[22:23]
	v_mfma_f32_16x16x32_bf16 v[164:167], v[140:143], v[40:43], v[104:107]
	v_mad_u64_u32 v[148:149], s[22:23], s24, v226, v[94:95]
	v_mfma_f32_16x16x32_bf16 v[104:107], v[144:147], v[44:47], 0
	v_lshl_add_u64 v[94:95], s[20:21], 0, v[92:93]
	v_lshl_add_u64 v[108:109], s[18:19], 0, v[92:93]
	v_mfma_f32_16x16x32_bf16 v[140:143], v[140:143], v[48:51], v[104:107]
	v_lshl_add_u64 v[150:151], s[12:13], 0, v[92:93]
	v_lshl_add_u64 v[154:155], s[8:9], 0, v[92:93]
	v_mfma_f32_16x16x32_bf16 v[104:107], v[136:139], v[20:23], 0
	s_add_i32 m0, s28, 13312
	s_nop 0
	global_load_lds_dwordx4 v[108:109], off
	s_add_i32 m0, s28, 12288
	s_nop 0
	global_load_lds_dwordx4 v[94:95], off
	s_add_i32 s44, s37, s38
	v_mfma_f32_16x16x32_bf16 v[180:183], v[132:135], v[24:27], v[104:107]
	s_nop 2
	s_add_i32 m0, s28, 15360
	s_nop 0
	global_load_lds_dwordx4 v[154:155], off
	s_add_i32 m0, s28, 14336
	s_nop 0
	global_load_lds_dwordx4 v[150:151], off
	s_add_i32 m0, s28, 4608
	s_nop 0
	global_load_lds_dwordx4 v[148:149], off offset:3584
	s_add_i32 m0, s28, 5568
	s_nop 0
	global_load_lds_dwordx4 v[148:149], off offset:3648
	v_add_co_u32_e32 v148, vcc, 0xa000, v148
	v_mfma_f32_16x16x32_bf16 v[144:147], v[136:139], v[28:31], 0
	s_nop 0
	v_addc_co_u32_e32 v149, vcc, 0, v149, vcc
	s_add_i32 m0, s28, 6656
	s_nop 0
	global_load_lds_dwordx4 v[148:149], off offset:3584
	s_add_i32 m0, s28, 7616
	s_nop 0
	global_load_lds_dwordx4 v[148:149], off offset:3648
	v_mfma_f32_16x16x32_bf16 v[172:175], v[132:135], v[32:35], v[144:147]
	s_add_i32 s6, s44, -8
	s_cmp_lt_u32 s6, -4
	s_cselect_b64 s[6:7], -1, 0
	v_mfma_f32_16x16x32_bf16 v[144:147], v[136:139], v[36:39], 0
	s_cmp_lt_u32 s38, s40
	s_cselect_b64 s[8:9], -1, 0
	s_and_b64 s[6:7], s[8:9], s[6:7]
	v_mfma_f32_16x16x32_bf16 v[136:139], v[136:139], v[44:47], 0
	s_andn2_b64 vcc, exec, s[6:7]
	v_add_u32_e32 v205, 64, v207
	v_mfma_f32_16x16x32_bf16 v[144:147], v[132:135], v[40:43], v[144:147]
	v_mfma_f32_16x16x32_bf16 v[132:135], v[132:135], v[48:51], v[136:139]
	s_cbranch_vccnz .LBB0_157
	v_add_u32_e32 v0, 48, v207
	v_cmp_gt_u32_e64 s[6:7], s93, v0
	v_add_u32_e32 v0, 49, v207
	v_cmp_gt_u32_e64 s[8:9], s93, v0
	v_add_u32_e32 v0, 50, v207
	v_cmp_gt_u32_e64 s[10:11], s93, v0
	v_add_u32_e32 v0, 51, v207
	v_cmp_gt_u32_e64 s[12:13], s93, v0
	s_nop 1
	v_cndmask_b32_e64 v176, v176, v227, s[6:7]
	v_cndmask_b32_e64 v177, v177, v227, s[8:9]
	v_cndmask_b32_e64 v178, v178, v227, s[10:11]
	v_cndmask_b32_e64 v179, v179, v227, s[12:13]
	v_add_u32_e32 v0, 32, v207
	v_cmp_gt_u32_e64 s[6:7], s93, v0
	v_add_u32_e32 v0, 33, v207
	v_cmp_gt_u32_e64 s[8:9], s93, v0
	v_add_u32_e32 v0, 34, v207
	v_cmp_gt_u32_e64 s[10:11], s93, v0
	v_add_u32_e32 v0, 35, v207
	v_cmp_gt_u32_e64 s[12:13], s93, v0
	s_nop 1
	v_cndmask_b32_e64 v168, v168, v227, s[6:7]
	v_cndmask_b32_e64 v169, v169, v227, s[8:9]
	v_cndmask_b32_e64 v170, v170, v227, s[10:11]
	v_cndmask_b32_e64 v171, v171, v227, s[12:13]
	v_add_u32_e32 v0, 16, v207
	v_cmp_gt_u32_e64 s[6:7], s93, v0
	v_add_u32_e32 v0, 17, v207
	v_cmp_gt_u32_e64 s[8:9], s93, v0
	v_add_u32_e32 v0, 18, v207
	v_cmp_gt_u32_e64 s[10:11], s93, v0
	v_add_u32_e32 v0, 19, v207
	v_cmp_gt_u32_e64 s[12:13], s93, v0
	s_nop 1
	v_cndmask_b32_e64 v164, v164, v227, s[6:7]
	v_cndmask_b32_e64 v165, v165, v227, s[8:9]
	v_cndmask_b32_e64 v166, v166, v227, s[10:11]
	v_cndmask_b32_e64 v167, v167, v227, s[12:13]
	v_add_u32_e32 v0, 0, v207
	v_cmp_gt_u32_e64 s[6:7], s93, v0
	v_add_u32_e32 v0, 1, v207
	v_cmp_gt_u32_e64 s[8:9], s93, v0
	v_add_u32_e32 v0, 2, v207
	v_cmp_gt_u32_e64 s[10:11], s93, v0
	v_add_u32_e32 v0, 3, v207
	v_cmp_gt_u32_e64 s[12:13], s93, v0
	s_nop 1
	v_cndmask_b32_e64 v140, v140, v227, s[6:7]
	v_cndmask_b32_e64 v141, v141, v227, s[8:9]
	v_cndmask_b32_e64 v142, v142, v227, s[10:11]
	v_cndmask_b32_e64 v143, v143, v227, s[12:13]
	v_add_u32_e32 v0, 52, v207
	v_cmp_gt_u32_e64 s[6:7], s93, v0
	v_add_u32_e32 v0, 53, v207
	v_cmp_gt_u32_e64 s[8:9], s93, v0
	v_add_u32_e32 v0, 54, v207
	v_cmp_gt_u32_e64 s[10:11], s93, v0
	v_add_u32_e32 v0, 55, v207
	v_cmp_gt_u32_e64 s[12:13], s93, v0
	s_nop 1
	v_cndmask_b32_e64 v180, v180, v227, s[6:7]
	v_cndmask_b32_e64 v181, v181, v227, s[8:9]
	v_cndmask_b32_e64 v182, v182, v227, s[10:11]
	v_cndmask_b32_e64 v183, v183, v227, s[12:13]
	v_add_u32_e32 v0, 36, v207
	v_cmp_gt_u32_e64 s[6:7], s93, v0
	v_add_u32_e32 v0, 37, v207
	v_cmp_gt_u32_e64 s[8:9], s93, v0
	v_add_u32_e32 v0, 38, v207
	v_cmp_gt_u32_e64 s[10:11], s93, v0
	v_add_u32_e32 v0, 39, v207
	v_cmp_gt_u32_e64 s[12:13], s93, v0
	s_nop 1
	v_cndmask_b32_e64 v172, v172, v227, s[6:7]
	v_cndmask_b32_e64 v173, v173, v227, s[8:9]
	v_cndmask_b32_e64 v174, v174, v227, s[10:11]
	v_cndmask_b32_e64 v175, v175, v227, s[12:13]
	v_add_u32_e32 v0, 20, v207
	v_cmp_gt_u32_e64 s[6:7], s93, v0
	v_add_u32_e32 v0, 21, v207
	v_cmp_gt_u32_e64 s[8:9], s93, v0
	v_add_u32_e32 v0, 22, v207
	v_cmp_gt_u32_e64 s[10:11], s93, v0
	v_add_u32_e32 v0, 23, v207
	v_cmp_gt_u32_e64 s[12:13], s93, v0
	s_nop 1
	v_cndmask_b32_e64 v144, v144, v227, s[6:7]
	v_cndmask_b32_e64 v145, v145, v227, s[8:9]
	v_cndmask_b32_e64 v146, v146, v227, s[10:11]
	v_cndmask_b32_e64 v147, v147, v227, s[12:13]
	v_add_u32_e32 v0, 4, v207
	v_cmp_gt_u32_e64 s[6:7], s93, v0
	v_add_u32_e32 v0, 5, v207
	v_cmp_gt_u32_e64 s[8:9], s93, v0
	v_add_u32_e32 v0, 6, v207
	v_cmp_gt_u32_e64 s[10:11], s93, v0
	v_add_u32_e32 v0, 7, v207
	v_cmp_gt_u32_e64 s[12:13], s93, v0
	s_nop 1
	v_cndmask_b32_e64 v132, v132, v227, s[6:7]
	v_cndmask_b32_e64 v133, v133, v227, s[8:9]
	v_cndmask_b32_e64 v134, v134, v227, s[10:11]
	v_cndmask_b32_e64 v135, v135, v227, s[12:13]
.LBB0_157:
	s_nop 1
	v_max_f32_e32 v0, v176, v177
	v_max_f32_e32 v136, v178, v179
	v_max_f32_e32 v137, v182, v183
	v_max3_f32 v137, v180, v181, v137
	v_max3_f32 v0, v0, v136, v137
	ds_bpermute_b32 v136, v199, v0
	s_waitcnt lgkmcnt(0)
	v_max_f32_e32 v0, v0, v136
	ds_bpermute_b32 v136, v195, v0
	s_add_i32 s45, s38, 2
	s_cmp_ge_u32 s45, s36
	s_cselect_b64 s[96:97], -1, 0
	s_waitcnt lgkmcnt(0)
	v_max3_f32 v206, v194, v0, v136
	v_sub_f32_e32 v136, v176, v206
	v_sub_f32_e32 v137, v177, v206
	v_sub_f32_e32 v0, v194, v206
	v_exp_f32_e32 v176, v136
	v_exp_f32_e32 v177, v137
	v_sub_f32_e32 v136, v178, v206
	v_sub_f32_e32 v137, v179, v206
	v_exp_f32_e32 v194, v0
	v_exp_f32_e32 v178, v136
	v_exp_f32_e32 v179, v137
	v_sub_f32_e32 v136, v180, v206
	v_sub_f32_e32 v137, v181, v206
	v_mul_f32_e32 v130, v130, v194
	v_mul_f32_e32 v131, v131, v194
	v_exp_f32_e32 v180, v136
	v_exp_f32_e32 v181, v137
	v_sub_f32_e32 v136, v182, v206
	v_sub_f32_e32 v137, v183, v206
	v_exp_f32_e32 v182, v136
	v_max_f32_e32 v136, v168, v169
	v_max_f32_e32 v138, v170, v171
	v_max_f32_e32 v139, v174, v175
	v_max3_f32 v139, v172, v173, v139
	v_max3_f32 v138, v136, v138, v139
	ds_bpermute_b32 v139, v199, v138
	v_mul_f32_e32 v128, v128, v194
	v_mul_f32_e32 v129, v129, v194
	v_exp_f32_e32 v183, v137
	v_cvt_pk_bf16_f32 v136, v176, v177
	v_cvt_pk_bf16_f32 v137, v178, v179
	s_waitcnt lgkmcnt(0)
	v_max_f32_e32 v0, v138, v139
	ds_bpermute_b32 v197, v195, v0
	v_cvt_pk_bf16_f32 v138, v180, v181
	v_cvt_pk_bf16_f32 v139, v182, v183
	s_cmp_lt_u32 s45, s36
	s_nop 0
	v_mfma_f32_16x16x32_bf16 v[128:131], v[84:87], v[136:139], v[128:131]
	s_waitcnt lgkmcnt(0)
	v_max3_f32 v204, v196, v0, v197
	v_sub_f32_e32 v0, v196, v204
	v_max_f32_e32 v196, v164, v165
	v_max_f32_e32 v197, v166, v167
	v_max_f32_e32 v200, v146, v147
	v_max3_f32 v200, v144, v145, v200
	v_max3_f32 v197, v196, v197, v200
	ds_bpermute_b32 v200, v199, v197
	v_exp_f32_e32 v196, v0
	v_sub_f32_e32 v168, v168, v204
	v_sub_f32_e32 v169, v169, v204
	v_sub_f32_e32 v170, v170, v204
	v_sub_f32_e32 v171, v171, v204
	s_waitcnt lgkmcnt(0)
	v_max_f32_e32 v0, v197, v200
	ds_bpermute_b32 v197, v195, v0
	v_sub_f32_e32 v172, v172, v204
	v_sub_f32_e32 v173, v173, v204
	v_sub_f32_e32 v174, v174, v204
	v_sub_f32_e32 v175, v175, v204
	v_exp_f32_e32 v168, v168
	v_exp_f32_e32 v169, v169
	s_waitcnt lgkmcnt(0)
	v_max3_f32 v200, v198, v0, v197
	v_mul_f32_e32 v98, v98, v196
	v_mul_f32_e32 v99, v99, v196
	v_mul_f32_e32 v96, v96, v196
	v_mul_f32_e32 v97, v97, v196
	v_sub_f32_e32 v0, v198, v200
	v_max_f32_e32 v197, v140, v141
	v_max_f32_e32 v198, v142, v143
	v_max_f32_e32 v203, v134, v135
	v_max3_f32 v203, v132, v133, v203
	v_max3_f32 v197, v197, v198, v203
	ds_bpermute_b32 v203, v199, v197
	v_exp_f32_e32 v198, v0
	v_sub_f32_e32 v164, v164, v200
	v_sub_f32_e32 v165, v165, v200
	v_sub_f32_e32 v166, v166, v200
	v_sub_f32_e32 v167, v167, v200
	v_sub_f32_e32 v144, v144, v200
	v_sub_f32_e32 v145, v145, v200
	s_waitcnt lgkmcnt(0)
	v_max_f32_e32 v0, v197, v203
	ds_bpermute_b32 v197, v195, v0
	v_sub_f32_e32 v146, v146, v200
	v_sub_f32_e32 v147, v147, v200
	v_mul_f32_e32 v58, v58, v198
	v_mul_f32_e32 v59, v59, v198
	v_mul_f32_e32 v56, v56, v198
	v_mul_f32_e32 v57, v57, v198
	v_exp_f32_e32 v170, v170
	s_waitcnt lgkmcnt(0)
	v_max3_f32 v0, v202, v0, v197
	v_sub_f32_e32 v197, v202, v0
	v_sub_f32_e32 v134, v134, v0
	v_sub_f32_e32 v135, v135, v0
	v_sub_f32_e32 v140, v140, v0
	v_sub_f32_e32 v141, v141, v0
	v_exp_f32_e32 v202, v134
	v_exp_f32_e32 v134, v197
	v_sub_f32_e32 v142, v142, v0
	v_sub_f32_e32 v143, v143, v0
	v_sub_f32_e32 v132, v132, v0
	v_sub_f32_e32 v133, v133, v0
	v_exp_f32_e32 v171, v171
	v_mul_f32_e32 v6, v6, v134
	v_mul_f32_e32 v7, v7, v134
	v_mul_f32_e32 v4, v4, v134
	v_mul_f32_e32 v5, v5, v134
	v_exp_f32_e32 v172, v172
	v_exp_f32_e32 v173, v173
	v_exp_f32_e32 v174, v174
	v_exp_f32_e32 v175, v175
	v_cvt_pk_bf16_f32 v208, v168, v169
	v_cvt_pk_bf16_f32 v209, v170, v171
	v_cvt_pk_bf16_f32 v210, v172, v173
	v_cvt_pk_bf16_f32 v211, v174, v175
	v_exp_f32_e32 v164, v164
	v_exp_f32_e32 v165, v165
	v_exp_f32_e32 v166, v166
	v_exp_f32_e32 v167, v167
	v_exp_f32_e32 v144, v144
	v_exp_f32_e32 v145, v145
	v_exp_f32_e32 v146, v146
	v_exp_f32_e32 v147, v147
	v_cvt_pk_bf16_f32 v212, v164, v165
	v_cvt_pk_bf16_f32 v213, v166, v167
	v_cvt_pk_bf16_f32 v214, v144, v145
	v_cvt_pk_bf16_f32 v215, v146, v147
	v_exp_f32_e32 v140, v140
	v_exp_f32_e32 v141, v141
	v_exp_f32_e32 v142, v142
	v_exp_f32_e32 v143, v143
	v_exp_f32_e32 v132, v132
	v_exp_f32_e32 v133, v133
	v_exp_f32_e32 v203, v135
	v_mfma_f32_16x16x32_bf16 v[96:99], v[84:87], v[208:211], v[96:99]
	v_cvt_pk_bf16_f32 v240, v140, v141
	v_cvt_pk_bf16_f32 v241, v142, v143
	v_cvt_pk_bf16_f32 v242, v132, v133
	v_mfma_f32_16x16x32_bf16 v[56:59], v[84:87], v[212:215], v[56:59]
	v_cvt_pk_bf16_f32 v243, v202, v203
	v_mul_f32_e64 v82, v82, v196
	v_mul_f32_e64 v83, v83, v196
	v_mul_f32_e32 v80, v80, v196
	v_mul_f32_e32 v81, v81, v196
	v_mfma_f32_16x16x32_bf16 v[4:7], v[84:87], v[240:243], v[4:7]
	v_mul_f32_e64 v86, v118, v194
	v_mul_f32_e64 v87, v119, v194
	v_mul_f32_e32 v84, v116, v194
	v_mul_f32_e32 v85, v117, v194
	v_mul_f32_e32 v54, v54, v198
	v_mul_f32_e32 v55, v55, v198
	v_mul_f32_e32 v52, v52, v198
	v_mul_f32_e32 v53, v53, v198
	v_mul_f32_e32 v10, v10, v134
	v_mul_f32_e32 v11, v11, v134
	v_mul_f32_e32 v8, v8, v134
	v_mul_f32_e32 v9, v9, v134
	v_mfma_f32_16x16x32_bf16 v[116:119], v[76:79], v[136:139], v[84:87]
	v_mul_f32_e64 v62, v62, v198
	v_mul_f32_e64 v63, v63, v198
	v_mul_f32_e32 v60, v60, v198
	v_mul_f32_e32 v61, v61, v198
	v_mul_f32_e32 v14, v14, v134
	v_mul_f32_e32 v15, v15, v134
	v_mfma_f32_16x16x32_bf16 v[80:83], v[76:79], v[208:211], v[80:83]
	v_mul_f32_e64 v12, v12, v134
	v_mul_f32_e64 v13, v13, v134
	v_mul_f32_e32 v66, v66, v198
	v_mul_f32_e32 v67, v67, v198
	v_mul_f32_e32 v64, v64, v198
	v_mul_f32_e32 v65, v65, v198
	v_mfma_f32_16x16x32_bf16 v[52:55], v[76:79], v[212:215], v[52:55]
	v_mul_f32_e64 v18, v18, v134
	v_mul_f32_e64 v19, v19, v134
	v_mul_f32_e32 v16, v16, v134
	v_mul_f32_e32 v17, v17, v134
	s_cselect_b32 s24, s45, s38
	v_mfma_f32_16x16x32_bf16 v[8:11], v[76:79], v[240:243], v[8:11]
	v_mul_f32_e64 v78, v122, v194
	v_mul_f32_e64 v79, v123, v194
	v_mul_f32_e32 v76, v120, v194
	v_mul_f32_e32 v77, v121, v194
	s_cmp_lt_i32 s24, s40
	v_mfma_f32_16x16x32_bf16 v[60:63], v[72:75], v[212:215], v[60:63]
	v_mfma_f32_16x16x32_bf16 v[120:123], v[72:75], v[136:139], v[76:79]
	s_nop 2
	v_mul_f32_e64 v78, v90, v196
	v_mul_f32_e64 v79, v91, v196
	v_mul_f32_e32 v76, v88, v196
	v_mul_f32_e32 v77, v89, v196
	v_mfma_f32_16x16x32_bf16 v[12:15], v[72:75], v[240:243], v[12:15]
	s_nop 0
	v_mfma_f32_16x16x32_bf16 v[88:91], v[72:75], v[208:211], v[76:79]
	v_mul_f32_e64 v74, v126, v194
	v_mul_f32_e64 v75, v127, v194
	v_mul_f32_e32 v72, v124, v194
	v_mul_f32_e32 v73, v125, v194
	v_mfma_f32_16x16x32_bf16 v[64:67], v[68:71], v[212:215], v[64:67]
	s_nop 0
	v_mfma_f32_16x16x32_bf16 v[124:127], v[68:71], v[136:139], v[72:75]
	s_nop 2
	v_mul_f32_e64 v74, v102, v196
	v_mul_f32_e64 v75, v103, v196
	v_mul_f32_e32 v72, v100, v196
	v_mul_f32_e32 v73, v101, v196
	v_mfma_f32_16x16x32_bf16 v[16:19], v[68:71], v[240:243], v[16:19]
	s_nop 0
	v_mfma_f32_16x16x32_bf16 v[100:103], v[68:71], v[208:211], v[72:75]
	s_cbranch_scc1 .LBB0_159
	s_sub_i32 s24, s24, s40
	s_mov_b64 s[8:9], 0x6000
	s_mov_b64 s[12:13], 0x4000
	s_mov_b64 s[18:19], 0x2000
	s_mov_b64 s[22:23], s[84:85]
	s_mov_b64 s[20:21], s[0:1]
	v_mov_b64_e32 v[68:69], v[188:189]
	s_branch .LBB0_160
.LBB0_159:
	s_mov_b64 s[8:9], 0x30000
	s_mov_b64 s[12:13], 0x20000
	s_mov_b64 s[18:19], 0x10000
	s_mov_b64 s[22:23], s[4:5]
	s_mov_b64 s[20:21], s[94:95]
	v_mov_b64_e32 v[68:69], v[190:191]
.LBB0_160:
	s_lshl_b32 s25, s24, 6
	s_add_u32 s20, s20, s25
	s_addc_u32 s21, s21, 0
	v_add_f32_e32 v70, v178, v176
	v_add_f32_e32 v71, v179, v177
	v_add_f32_e32 v72, v170, v168
	v_add_f32_e32 v73, v171, v169
	s_add_u32 s18, s20, s18
	v_add_f32_e32 v70, v180, v70
	v_add_f32_e32 v71, v181, v71
	v_add_f32_e32 v72, v172, v72
	v_add_f32_e32 v73, v173, v73
	s_addc_u32 s19, s21, s19
	v_add_f32_e32 v70, v182, v70
	v_add_f32_e32 v71, v183, v71
	v_add_f32_e32 v72, v174, v72
	v_add_f32_e32 v73, v175, v73
	v_mov_b32_e32 v74, v72
	v_mov_b32_e32 v75, v70
	v_mov_b32_e32 v70, v73
	v_mov_b32_e32 v197, v194
	v_add_f32_e32 v70, v74, v70
	v_add_f32_e32 v71, v75, v71
	s_add_u32 s12, s20, s12
	v_fma_f32 v2, v2, v196, v70
	v_fma_f32 v3, v3, v197, v71
	s_addc_u32 s13, s21, s13
	v_add_f32_e32 v70, v166, v164
	v_add_f32_e32 v71, v167, v165
	v_add_f32_e32 v72, v142, v140
	v_add_f32_e32 v73, v143, v141
	v_add_f32_e32 v70, v144, v70
	v_add_f32_e32 v71, v145, v71
	v_add_f32_e32 v72, v132, v72
	v_add_f32_e32 v73, v133, v73
	v_add_f32_e32 v70, v146, v70
	v_add_f32_e32 v71, v147, v71
	v_add_f32_e32 v72, v202, v72
	v_add_f32_e32 v73, v203, v73
	s_add_u32 s8, s20, s8
	v_mov_b32_e32 v74, v72
	v_mov_b32_e32 v75, v70
	v_mov_b32_e32 v70, v73
	s_addc_u32 s9, s21, s9
	v_mov_b32_e32 v135, v198
	v_add_f32_e32 v70, v74, v70
	v_add_f32_e32 v71, v75, v71
	v_fma_f32 v186, v186, v134, v70
	v_fma_f32 v187, v187, v135, v71
	v_lshl_add_u64 v[70:71], v[192:193], 0, s[22:23]
	v_mad_u64_u32 v[144:145], s[22:23], s24, v226, v[70:71]
	v_lshl_add_u64 v[72:73], s[20:21], 0, v[68:69]
	v_lshl_add_u64 v[76:77], s[18:19], 0, v[68:69]
	v_lshl_add_u64 v[132:133], s[12:13], 0, v[68:69]
	v_lshl_add_u64 v[134:135], s[8:9], 0, v[68:69]
	s_add_i32 m0, s28, 4096
	s_nop 0
	global_load_lds_dwordx4 v[72:73], off
	s_add_i32 m0, s28, 5120
	s_nop 0
	global_load_lds_dwordx4 v[76:77], off
	s_add_i32 m0, s28, 6144
	s_nop 0
	global_load_lds_dwordx4 v[132:133], off
	s_add_i32 m0, s28, 7168
	s_nop 0
	global_load_lds_dwordx4 v[134:135], off
	v_add_co_u32_e32 v136, vcc, 0xa000, v144
	s_nop 1
	v_addc_co_u32_e32 v137, vcc, 0, v145, vcc
	s_add_i32 m0, s28, -576
	s_nop 0
	global_load_lds_dwordx4 v[136:137], off offset:3648
	s_add_i32 m0, s28, -1536
	s_nop 0
	global_load_lds_dwordx4 v[136:137], off offset:3584
	s_add_i32 m0, s28, -2624
	s_nop 0
	global_load_lds_dwordx4 v[144:145], off offset:3648
	s_add_i32 m0, s28, -3584
	s_nop 0
	global_load_lds_dwordx4 v[144:145], off offset:3584
	s_andn2_b64 vcc, exec, s[34:35]
	s_cbranch_vccnz .LBB0_164
	s_waitcnt vmcnt(8)
	ds_read_b128 v[156:159], v216 offset:8192
	ds_read_b128 v[160:163], v216 offset:9216
	ds_read_b128 v[152:155], v216 offset:10240
	ds_read_b128 v[148:151], v216 offset:11264
	ds_read_b128 v[112:115], v216 offset:12288
	ds_read_b128 v[108:111], v216 offset:13312
	ds_read_b128 v[104:107], v216 offset:14336
	ds_read_b128 v[92:95], v216 offset:15360
	s_waitcnt lgkmcnt(4)
	v_mfma_f32_16x16x32_bf16 v[164:167], v[156:159], v[20:23], 0
	s_add_i32 s44, s44, -7
	s_cmp_lt_u32 s44, -4
	s_cselect_b64 s[6:7], -1, 0
	s_waitcnt vmcnt(10)
	v_mfma_f32_16x16x32_bf16 v[180:183], v[160:163], v[24:27], v[164:167]
	s_cmp_lt_u32 s42, s40
	s_cselect_b64 s[8:9], -1, 0
	s_and_b64 s[6:7], s[8:9], s[6:7]
	v_mfma_f32_16x16x32_bf16 v[164:167], v[156:159], v[28:31], 0
	s_andn2_b64 vcc, exec, s[6:7]
	v_mfma_f32_16x16x32_bf16 v[172:175], v[160:163], v[32:35], v[164:167]
	v_mfma_f32_16x16x32_bf16 v[164:167], v[156:159], v[36:39], 0
	v_mfma_f32_16x16x32_bf16 v[156:159], v[156:159], v[44:47], 0
	v_mfma_f32_16x16x32_bf16 v[168:171], v[160:163], v[40:43], v[164:167]
	v_mfma_f32_16x16x32_bf16 v[156:159], v[160:163], v[48:51], v[156:159]
	s_waitcnt vmcnt(9)
	v_mfma_f32_16x16x32_bf16 v[160:163], v[152:155], v[20:23], 0
	s_waitcnt vmcnt(8)
	v_mfma_f32_16x16x32_bf16 v[176:179], v[148:151], v[24:27], v[160:163]
	v_mfma_f32_16x16x32_bf16 v[160:163], v[152:155], v[28:31], 0
	v_mfma_f32_16x16x32_bf16 v[164:167], v[152:155], v[36:39], 0
	v_mfma_f32_16x16x32_bf16 v[152:155], v[152:155], v[44:47], 0
	v_mfma_f32_16x16x32_bf16 v[160:163], v[148:151], v[32:35], v[160:163]
	v_mfma_f32_16x16x32_bf16 v[164:167], v[148:151], v[40:43], v[164:167]
	v_mfma_f32_16x16x32_bf16 v[152:155], v[148:151], v[48:51], v[152:155]
	s_cbranch_vccnz .LBB0_163
	v_add_u32_e32 v148, 80, v207
	v_cmp_gt_u32_e64 s[6:7], s93, v148
	v_add_u32_e32 v148, 81, v207
	v_cmp_gt_u32_e64 s[8:9], s93, v148
	v_add_u32_e32 v148, 82, v207
	v_cmp_gt_u32_e64 s[10:11], s93, v148
	v_add_u32_e32 v148, 83, v207
	v_cmp_gt_u32_e64 s[12:13], s93, v148
	s_nop 1
	v_cndmask_b32_e64 v180, v180, v227, s[6:7]
	v_cndmask_b32_e64 v181, v181, v227, s[8:9]
	v_cndmask_b32_e64 v182, v182, v227, s[10:11]
	v_cndmask_b32_e64 v183, v183, v227, s[12:13]
	v_add_u32_e32 v148, 64, v207
	v_cmp_gt_u32_e64 s[6:7], s93, v148
	v_add_u32_e32 v148, 65, v207
	v_cmp_gt_u32_e64 s[8:9], s93, v148
	v_add_u32_e32 v148, 66, v207
	v_cmp_gt_u32_e64 s[10:11], s93, v148
	v_add_u32_e32 v148, 67, v207
	v_cmp_gt_u32_e64 s[12:13], s93, v148
	s_nop 1
	v_cndmask_b32_e64 v172, v172, v227, s[6:7]
	v_cndmask_b32_e64 v173, v173, v227, s[8:9]
	v_cndmask_b32_e64 v174, v174, v227, s[10:11]
	v_cndmask_b32_e64 v175, v175, v227, s[12:13]
	v_add_u32_e32 v148, 48, v207
	v_cmp_gt_u32_e64 s[6:7], s93, v148
	v_add_u32_e32 v148, 49, v207
	v_cmp_gt_u32_e64 s[8:9], s93, v148
	v_add_u32_e32 v148, 50, v207
	v_cmp_gt_u32_e64 s[10:11], s93, v148
	v_add_u32_e32 v148, 51, v207
	v_cmp_gt_u32_e64 s[12:13], s93, v148
	s_nop 1
	v_cndmask_b32_e64 v168, v168, v227, s[6:7]
	v_cndmask_b32_e64 v169, v169, v227, s[8:9]
	v_cndmask_b32_e64 v170, v170, v227, s[10:11]
	v_cndmask_b32_e64 v171, v171, v227, s[12:13]
	v_add_u32_e32 v148, 32, v207
	v_cmp_gt_u32_e64 s[6:7], s93, v148
	v_add_u32_e32 v148, 33, v207
	v_cmp_gt_u32_e64 s[8:9], s93, v148
	v_add_u32_e32 v148, 34, v207
	v_cmp_gt_u32_e64 s[10:11], s93, v148
	v_add_u32_e32 v148, 35, v207
	v_cmp_gt_u32_e64 s[12:13], s93, v148
	s_nop 1
	v_cndmask_b32_e64 v156, v156, v227, s[6:7]
	v_cndmask_b32_e64 v157, v157, v227, s[8:9]
	v_cndmask_b32_e64 v158, v158, v227, s[10:11]
	v_cndmask_b32_e64 v159, v159, v227, s[12:13]
	v_add_u32_e32 v148, 84, v207
	v_cmp_gt_u32_e64 s[6:7], s93, v148
	v_add_u32_e32 v148, 85, v207
	v_cmp_gt_u32_e64 s[8:9], s93, v148
	v_add_u32_e32 v148, 86, v207
	v_cmp_gt_u32_e64 s[10:11], s93, v148
	v_add_u32_e32 v148, 87, v207
	v_cmp_gt_u32_e64 s[12:13], s93, v148
	s_nop 1
	v_cndmask_b32_e64 v176, v176, v227, s[6:7]
	v_cndmask_b32_e64 v177, v177, v227, s[8:9]
	v_cndmask_b32_e64 v178, v178, v227, s[10:11]
	v_cndmask_b32_e64 v179, v179, v227, s[12:13]
	v_add_u32_e32 v148, 68, v207
	v_cmp_gt_u32_e64 s[6:7], s93, v148
	v_add_u32_e32 v148, 69, v207
	v_cmp_gt_u32_e64 s[8:9], s93, v148
	v_add_u32_e32 v148, 70, v207
	v_cmp_gt_u32_e64 s[10:11], s93, v148
	v_add_u32_e32 v148, 71, v207
	v_cmp_gt_u32_e64 s[12:13], s93, v148
	s_nop 1
	v_cndmask_b32_e64 v160, v160, v227, s[6:7]
	v_cndmask_b32_e64 v161, v161, v227, s[8:9]
	v_cndmask_b32_e64 v162, v162, v227, s[10:11]
	v_cndmask_b32_e64 v163, v163, v227, s[12:13]
	v_add_u32_e32 v148, 52, v207
	v_cmp_gt_u32_e64 s[6:7], s93, v148
	v_add_u32_e32 v148, 53, v207
	v_cmp_gt_u32_e64 s[8:9], s93, v148
	v_add_u32_e32 v148, 54, v207
	v_cmp_gt_u32_e64 s[10:11], s93, v148
	v_add_u32_e32 v148, 55, v207
	v_cmp_gt_u32_e64 s[12:13], s93, v148
	s_nop 1
	v_cndmask_b32_e64 v164, v164, v227, s[6:7]
	v_cndmask_b32_e64 v165, v165, v227, s[8:9]
	v_cndmask_b32_e64 v166, v166, v227, s[10:11]
	v_cndmask_b32_e64 v167, v167, v227, s[12:13]
	v_add_u32_e32 v148, 36, v207
	v_cmp_gt_u32_e64 s[6:7], s93, v148
	v_add_u32_e32 v148, 37, v207
	v_cmp_gt_u32_e64 s[8:9], s93, v148
	v_add_u32_e32 v148, 38, v207
	v_cmp_gt_u32_e64 s[10:11], s93, v148
	v_add_u32_e32 v148, 39, v207
	v_cmp_gt_u32_e64 s[12:13], s93, v148
	s_nop 1
	v_cndmask_b32_e64 v152, v152, v227, s[6:7]
	v_cndmask_b32_e64 v153, v153, v227, s[8:9]
	v_cndmask_b32_e64 v154, v154, v227, s[10:11]
	v_cndmask_b32_e64 v155, v155, v227, s[12:13]
